# GEMM main loops: hipcc's per-phase s_setprio flips removed (timing-only A/B)
# speedup vs baseline: 1.0055x; 1.0055x over previous
.LBB0_98:
	s_add_u32 s4, s44, 0xfffc0080
	s_addc_u32 s5, s45, -1
	s_add_i32 s12, 0, 0x10000
	v_add_u32_e32 v140, s12, v143
	ds_read_b128 v[146:149], v140
	ds_read_b128 v[150:153], v140 offset:1024
	ds_read_b128 v[154:157], v140 offset:2048
	ds_read_b128 v[158:161], v140 offset:3072
	s_cmp_eq_u32 s55, 12
	s_cselect_b32 s49, s23, s5
	s_cselect_b32 s48, s51, s4
	s_cselect_b32 s47, s25, s54
	s_cselect_b32 s46, s52, s53
	v_lshl_add_u64 v[140:141], s[44:45], 0, v[136:137]
	s_add_i32 m0, s11, 0xc000
	ds_read_b128 v[162:165], v145
	ds_read_b128 v[166:169], v145 offset:1024
	ds_read_b128 v[176:179], v145 offset:2048
	ds_read_b128 v[180:183], v145 offset:3072
	ds_read_b128 v[184:187], v145 offset:4096
	ds_read_b128 v[188:191], v145 offset:5120
	ds_read_b128 v[192:195], v145 offset:6144
	ds_read_b128 v[196:199], v145 offset:7168
	global_load_lds_dwordx4 v[140:141], off
	v_lshl_add_u64 v[140:141], s[44:45], 0, v[138:139]
	s_add_i32 m0, s11, 0xe000
	s_nop 0
	global_load_lds_dwordx4 v[140:141], off
	s_waitcnt lgkmcnt(8)
	s_barrier
	s_waitcnt lgkmcnt(0)
	s_waitcnt lgkmcnt(0)
	v_mfma_f32_16x16x32_bf16 v[126:129], v[146:149], v[162:165], v[126:129]
	v_mfma_f32_16x16x32_bf16 v[118:121], v[154:157], v[162:165], v[118:121]
	v_mfma_f32_16x16x32_bf16 v[110:113], v[146:149], v[176:179], v[110:113]
	v_mfma_f32_16x16x32_bf16 v[102:105], v[154:157], v[176:179], v[102:105]
	v_mfma_f32_16x16x32_bf16 v[94:97], v[146:149], v[184:187], v[94:97]
	v_mfma_f32_16x16x32_bf16 v[86:89], v[154:157], v[184:187], v[86:89]
	v_mfma_f32_16x16x32_bf16 v[78:81], v[146:149], v[192:195], v[78:81]
	v_mfma_f32_16x16x32_bf16 v[70:73], v[154:157], v[192:195], v[70:73]
	v_mfma_f32_16x16x32_bf16 v[126:129], v[150:153], v[166:169], v[126:129]
	v_mfma_f32_16x16x32_bf16 v[118:121], v[158:161], v[166:169], v[118:121]
	v_mfma_f32_16x16x32_bf16 v[110:113], v[150:153], v[180:183], v[110:113]
	v_mfma_f32_16x16x32_bf16 v[102:105], v[158:161], v[180:183], v[102:105]
	v_mfma_f32_16x16x32_bf16 v[94:97], v[150:153], v[188:191], v[94:97]
	v_mfma_f32_16x16x32_bf16 v[86:89], v[158:161], v[188:191], v[86:89]
	v_mfma_f32_16x16x32_bf16 v[78:81], v[150:153], v[196:199], v[78:81]
	v_mfma_f32_16x16x32_bf16 v[70:73], v[158:161], v[196:199], v[70:73]
	s_barrier
	s_add_i32 s13, 0, 0x14000
	v_add_u32_e32 v140, s13, v143
	s_add_i32 s4, s12, s6
	ds_read_b128 v[228:231], v140
	ds_read_b128 v[232:235], v140 offset:1024
	ds_read_b128 v[236:239], v140 offset:2048
	ds_read_b128 v[240:243], v140 offset:3072
	v_lshl_add_u64 v[140:141], s[46:47], 0, v[0:1]
	s_mov_b32 m0, s4
	v_lshl_add_u64 v[200:201], s[46:47], 0, v[130:131]
	global_load_lds_dwordx4 v[140:141], off
	s_add_i32 m0, s4, 0x2000
	s_nop 0
	global_load_lds_dwordx4 v[200:201], off
	s_barrier
	s_waitcnt lgkmcnt(0)
	s_waitcnt lgkmcnt(0)
	v_mfma_f32_16x16x32_bf16 v[122:125], v[228:231], v[162:165], v[122:125]
	v_mfma_f32_16x16x32_bf16 v[114:117], v[236:239], v[162:165], v[114:117]
	v_mfma_f32_16x16x32_bf16 v[106:109], v[228:231], v[176:179], v[106:109]
	v_mfma_f32_16x16x32_bf16 v[98:101], v[236:239], v[176:179], v[98:101]
	v_mfma_f32_16x16x32_bf16 v[90:93], v[228:231], v[184:187], v[90:93]
	v_mfma_f32_16x16x32_bf16 v[82:85], v[236:239], v[184:187], v[82:85]
	v_mfma_f32_16x16x32_bf16 v[74:77], v[228:231], v[192:195], v[74:77]
	v_mfma_f32_16x16x32_bf16 v[66:69], v[236:239], v[192:195], v[66:69]
	v_mfma_f32_16x16x32_bf16 v[122:125], v[232:235], v[166:169], v[122:125]
	v_mfma_f32_16x16x32_bf16 v[114:117], v[240:243], v[166:169], v[114:117]
	v_mfma_f32_16x16x32_bf16 v[106:109], v[232:235], v[180:183], v[106:109]
	v_mfma_f32_16x16x32_bf16 v[98:101], v[240:243], v[180:183], v[98:101]
	v_mfma_f32_16x16x32_bf16 v[90:93], v[232:235], v[188:191], v[90:93]
	v_mfma_f32_16x16x32_bf16 v[82:85], v[240:243], v[188:191], v[82:85]
	v_mfma_f32_16x16x32_bf16 v[74:77], v[232:235], v[196:199], v[74:77]
	v_mfma_f32_16x16x32_bf16 v[66:69], v[240:243], v[196:199], v[66:69]
	s_mov_b32 m0, s11
	v_lshl_add_u64 v[244:245], s[48:49], 0, v[134:135]
	s_barrier
	ds_read_b128 v[162:165], v145 offset:16384
	ds_read_b128 v[166:169], v145 offset:17408
	ds_read_b128 v[176:179], v145 offset:18432
	ds_read_b128 v[180:183], v145 offset:19456
	ds_read_b128 v[184:187], v145 offset:20480
	ds_read_b128 v[188:191], v145 offset:21504
	ds_read_b128 v[192:195], v145 offset:22528
	ds_read_b128 v[196:199], v145 offset:23552
	global_load_lds_dwordx4 v[244:245], off
	v_lshl_add_u64 v[246:247], s[48:49], 0, v[132:133]
	s_mov_b32 m0, s14
	s_nop 0
	global_load_lds_dwordx4 v[246:247], off
	s_barrier
	s_waitcnt lgkmcnt(0)
	s_waitcnt lgkmcnt(0)
	v_mfma_f32_16x16x32_bf16 v[62:65], v[146:149], v[162:165], v[62:65]
	v_mfma_f32_16x16x32_bf16 v[54:57], v[154:157], v[162:165], v[54:57]
	v_mfma_f32_16x16x32_bf16 v[46:49], v[146:149], v[176:179], v[46:49]
	v_mfma_f32_16x16x32_bf16 v[38:41], v[154:157], v[176:179], v[38:41]
	v_mfma_f32_16x16x32_bf16 v[30:33], v[146:149], v[184:187], v[30:33]
	v_mfma_f32_16x16x32_bf16 v[22:25], v[154:157], v[184:187], v[22:25]
	v_mfma_f32_16x16x32_bf16 v[14:17], v[146:149], v[192:195], v[14:17]
	v_mfma_f32_16x16x32_bf16 v[6:9], v[154:157], v[192:195], v[6:9]
	v_mfma_f32_16x16x32_bf16 v[62:65], v[150:153], v[166:169], v[62:65]
	v_mfma_f32_16x16x32_bf16 v[54:57], v[158:161], v[166:169], v[54:57]
	v_mfma_f32_16x16x32_bf16 v[46:49], v[150:153], v[180:183], v[46:49]
	v_mfma_f32_16x16x32_bf16 v[38:41], v[158:161], v[180:183], v[38:41]
	v_mfma_f32_16x16x32_bf16 v[30:33], v[150:153], v[188:191], v[30:33]
	v_mfma_f32_16x16x32_bf16 v[22:25], v[158:161], v[188:191], v[22:25]
	v_mfma_f32_16x16x32_bf16 v[14:17], v[150:153], v[196:199], v[14:17]
	v_mfma_f32_16x16x32_bf16 v[6:9], v[158:161], v[196:199], v[6:9]
	s_barrier
	s_add_u32 s4, s46, 0x40000
	s_addc_u32 s5, s47, 0
	s_add_i32 s12, s13, s6
	v_lshl_add_u64 v[146:147], s[4:5], 0, v[0:1]
	s_mov_b32 m0, s12
	s_nop 0
	global_load_lds_dwordx4 v[146:147], off
	v_lshl_add_u64 v[146:147], s[4:5], 0, v[130:131]
	s_add_i32 m0, s12, 0x2000
	s_nop 0
	global_load_lds_dwordx4 v[146:147], off
	s_waitcnt vmcnt(6)
	s_barrier
	v_mfma_f32_16x16x32_bf16 v[58:61], v[228:231], v[162:165], v[58:61]
	v_mfma_f32_16x16x32_bf16 v[50:53], v[236:239], v[162:165], v[50:53]
	v_mfma_f32_16x16x32_bf16 v[42:45], v[228:231], v[176:179], v[42:45]
	v_mfma_f32_16x16x32_bf16 v[34:37], v[236:239], v[176:179], v[34:37]
	v_mfma_f32_16x16x32_bf16 v[26:29], v[228:231], v[184:187], v[26:29]
	v_mfma_f32_16x16x32_bf16 v[18:21], v[236:239], v[184:187], v[18:21]
	v_mfma_f32_16x16x32_bf16 v[10:13], v[228:231], v[192:195], v[10:13]
	v_mfma_f32_16x16x32_bf16 v[2:5], v[236:239], v[192:195], v[2:5]
	v_mfma_f32_16x16x32_bf16 v[58:61], v[232:235], v[166:169], v[58:61]
	v_mfma_f32_16x16x32_bf16 v[50:53], v[240:243], v[166:169], v[50:53]
	v_mfma_f32_16x16x32_bf16 v[42:45], v[232:235], v[180:183], v[42:45]
	v_mfma_f32_16x16x32_bf16 v[34:37], v[240:243], v[180:183], v[34:37]
	v_mfma_f32_16x16x32_bf16 v[26:29], v[232:235], v[188:191], v[26:29]
	v_mfma_f32_16x16x32_bf16 v[18:21], v[240:243], v[188:191], v[18:21]
	v_mfma_f32_16x16x32_bf16 v[10:13], v[232:235], v[196:199], v[10:13]
	v_mfma_f32_16x16x32_bf16 v[2:5], v[240:243], v[196:199], v[2:5]
	s_add_i32 s12, 0, 0x18000
	v_add_u32_e32 v158, s12, v143
	s_barrier
	ds_read_b128 v[146:149], v158
	ds_read_b128 v[150:153], v158 offset:1024
	ds_read_b128 v[154:157], v158 offset:2048
	ds_read_b128 v[158:161], v158 offset:3072
	s_add_u32 s4, s48, 0x40000
	s_addc_u32 s5, s49, 0
	s_mov_b32 m0, s15
	v_lshl_add_u64 v[228:229], s[4:5], 0, v[134:135]
	ds_read_b128 v[162:165], v145 offset:32768
	ds_read_b128 v[166:169], v145 offset:33792
	ds_read_b128 v[176:179], v145 offset:34816
	ds_read_b128 v[180:183], v145 offset:35840
	ds_read_b128 v[184:187], v145 offset:36864
	ds_read_b128 v[188:191], v145 offset:37888
	ds_read_b128 v[192:195], v145 offset:38912
	ds_read_b128 v[196:199], v145 offset:39936
	global_load_lds_dwordx4 v[228:229], off
	v_lshl_add_u64 v[228:229], s[4:5], 0, v[132:133]
	s_mov_b32 m0, s18
	s_nop 0
	global_load_lds_dwordx4 v[228:229], off
	s_waitcnt lgkmcnt(8)
	s_barrier
	s_waitcnt lgkmcnt(0)
	s_waitcnt lgkmcnt(0)
	v_mfma_f32_16x16x32_bf16 v[126:129], v[146:149], v[162:165], v[126:129]
	v_mfma_f32_16x16x32_bf16 v[118:121], v[154:157], v[162:165], v[118:121]
	v_mfma_f32_16x16x32_bf16 v[110:113], v[146:149], v[176:179], v[110:113]
	v_mfma_f32_16x16x32_bf16 v[102:105], v[154:157], v[176:179], v[102:105]
	v_mfma_f32_16x16x32_bf16 v[94:97], v[146:149], v[184:187], v[94:97]
	v_mfma_f32_16x16x32_bf16 v[86:89], v[154:157], v[184:187], v[86:89]
	v_mfma_f32_16x16x32_bf16 v[78:81], v[146:149], v[192:195], v[78:81]
	v_mfma_f32_16x16x32_bf16 v[70:73], v[154:157], v[192:195], v[70:73]
	v_mfma_f32_16x16x32_bf16 v[126:129], v[150:153], v[166:169], v[126:129]
	v_mfma_f32_16x16x32_bf16 v[118:121], v[158:161], v[166:169], v[118:121]
	v_mfma_f32_16x16x32_bf16 v[110:113], v[150:153], v[180:183], v[110:113]
	v_mfma_f32_16x16x32_bf16 v[102:105], v[158:161], v[180:183], v[102:105]
	v_mfma_f32_16x16x32_bf16 v[94:97], v[150:153], v[188:191], v[94:97]
	v_mfma_f32_16x16x32_bf16 v[86:89], v[158:161], v[188:191], v[86:89]
	v_mfma_f32_16x16x32_bf16 v[78:81], v[150:153], v[196:199], v[78:81]
	v_mfma_f32_16x16x32_bf16 v[70:73], v[158:161], v[196:199], v[70:73]
	s_barrier
	s_add_i32 s13, 0, 0x1c000
	s_add_i32 s4, s12, s6
	v_add_u32_e32 v175, s13, v143
	v_lshl_add_u64 v[140:141], v[140:141], 0, s[34:35]
	s_mov_b32 m0, s4
	ds_read_b128 v[228:231], v175
	ds_read_b128 v[232:235], v175 offset:1024
	ds_read_b128 v[236:239], v175 offset:2048
	ds_read_b128 v[240:243], v175 offset:3072
	global_load_lds_dwordx4 v[140:141], off
	v_lshl_add_u64 v[140:141], v[200:201], 0, s[34:35]
	s_add_i32 m0, s4, 0x2000
	s_nop 0
	global_load_lds_dwordx4 v[140:141], off
	s_barrier
	s_waitcnt lgkmcnt(0)
	s_waitcnt lgkmcnt(0)
	v_mfma_f32_16x16x32_bf16 v[122:125], v[228:231], v[162:165], v[122:125]
	v_mfma_f32_16x16x32_bf16 v[114:117], v[236:239], v[162:165], v[114:117]
	v_mfma_f32_16x16x32_bf16 v[106:109], v[228:231], v[176:179], v[106:109]
	v_mfma_f32_16x16x32_bf16 v[98:101], v[236:239], v[176:179], v[98:101]
	v_mfma_f32_16x16x32_bf16 v[90:93], v[228:231], v[184:187], v[90:93]
	v_mfma_f32_16x16x32_bf16 v[82:85], v[236:239], v[184:187], v[82:85]
	v_mfma_f32_16x16x32_bf16 v[74:77], v[228:231], v[192:195], v[74:77]
	v_mfma_f32_16x16x32_bf16 v[66:69], v[236:239], v[192:195], v[66:69]
	v_mfma_f32_16x16x32_bf16 v[122:125], v[232:235], v[166:169], v[122:125]
	v_mfma_f32_16x16x32_bf16 v[114:117], v[240:243], v[166:169], v[114:117]
	v_mfma_f32_16x16x32_bf16 v[106:109], v[232:235], v[180:183], v[106:109]
	v_mfma_f32_16x16x32_bf16 v[98:101], v[240:243], v[180:183], v[98:101]
	v_mfma_f32_16x16x32_bf16 v[90:93], v[232:235], v[188:191], v[90:93]
	v_mfma_f32_16x16x32_bf16 v[82:85], v[240:243], v[188:191], v[82:85]
	v_mfma_f32_16x16x32_bf16 v[74:77], v[232:235], v[196:199], v[74:77]
	v_mfma_f32_16x16x32_bf16 v[66:69], v[240:243], v[196:199], v[66:69]
	s_mov_b32 m0, s20
	v_lshl_add_u64 v[140:141], v[244:245], 0, s[34:35]
	s_barrier
	ds_read_b128 v[162:165], v145 offset:49152
	ds_read_b128 v[166:169], v145 offset:50176
	ds_read_b128 v[176:179], v145 offset:51200
	ds_read_b128 v[180:183], v145 offset:52224
	ds_read_b128 v[184:187], v145 offset:53248
	ds_read_b128 v[188:191], v145 offset:54272
	ds_read_b128 v[192:195], v145 offset:55296
	ds_read_b128 v[196:199], v145 offset:56320
	global_load_lds_dwordx4 v[140:141], off
	v_lshl_add_u64 v[140:141], v[246:247], 0, s[34:35]
	s_mov_b32 m0, s21
	s_nop 0
	global_load_lds_dwordx4 v[140:141], off
	s_barrier
	s_waitcnt lgkmcnt(0)
	s_waitcnt lgkmcnt(0)
	v_mfma_f32_16x16x32_bf16 v[62:65], v[146:149], v[162:165], v[62:65]
	v_mfma_f32_16x16x32_bf16 v[54:57], v[154:157], v[162:165], v[54:57]
	v_mfma_f32_16x16x32_bf16 v[46:49], v[146:149], v[176:179], v[46:49]
	v_mfma_f32_16x16x32_bf16 v[38:41], v[154:157], v[176:179], v[38:41]
	v_mfma_f32_16x16x32_bf16 v[30:33], v[146:149], v[184:187], v[30:33]
	v_mfma_f32_16x16x32_bf16 v[22:25], v[154:157], v[184:187], v[22:25]
	v_mfma_f32_16x16x32_bf16 v[14:17], v[146:149], v[192:195], v[14:17]
	v_mfma_f32_16x16x32_bf16 v[6:9], v[154:157], v[192:195], v[6:9]
	v_mfma_f32_16x16x32_bf16 v[62:65], v[150:153], v[166:169], v[62:65]
	v_mfma_f32_16x16x32_bf16 v[54:57], v[158:161], v[166:169], v[54:57]
	v_mfma_f32_16x16x32_bf16 v[46:49], v[150:153], v[180:183], v[46:49]
	v_mfma_f32_16x16x32_bf16 v[38:41], v[158:161], v[180:183], v[38:41]
	v_mfma_f32_16x16x32_bf16 v[30:33], v[150:153], v[188:191], v[30:33]
	v_mfma_f32_16x16x32_bf16 v[22:25], v[158:161], v[188:191], v[22:25]
	v_mfma_f32_16x16x32_bf16 v[14:17], v[150:153], v[196:199], v[14:17]
	v_mfma_f32_16x16x32_bf16 v[6:9], v[158:161], v[196:199], v[6:9]
	s_barrier
	s_add_u32 s4, s46, 0x40080
	s_addc_u32 s5, s47, 0
	s_add_i32 s12, s13, s6
	v_lshl_add_u64 v[140:141], s[4:5], 0, v[0:1]
	s_mov_b32 m0, s12
	s_nop 0
	global_load_lds_dwordx4 v[140:141], off
	v_lshl_add_u64 v[140:141], s[4:5], 0, v[130:131]
	s_add_i32 m0, s12, 0x2000
	s_nop 0
	global_load_lds_dwordx4 v[140:141], off
	s_waitcnt vmcnt(6)
	s_barrier
	v_mfma_f32_16x16x32_bf16 v[58:61], v[228:231], v[162:165], v[58:61]
	v_mfma_f32_16x16x32_bf16 v[50:53], v[236:239], v[162:165], v[50:53]
	v_mfma_f32_16x16x32_bf16 v[42:45], v[228:231], v[176:179], v[42:45]
	v_mfma_f32_16x16x32_bf16 v[34:37], v[236:239], v[176:179], v[34:37]
	v_mfma_f32_16x16x32_bf16 v[26:29], v[228:231], v[184:187], v[26:29]
	v_mfma_f32_16x16x32_bf16 v[18:21], v[236:239], v[184:187], v[18:21]
	v_mfma_f32_16x16x32_bf16 v[10:13], v[228:231], v[192:195], v[10:13]
	v_mfma_f32_16x16x32_bf16 v[2:5], v[236:239], v[192:195], v[2:5]
	v_mfma_f32_16x16x32_bf16 v[58:61], v[232:235], v[166:169], v[58:61]
	v_mfma_f32_16x16x32_bf16 v[50:53], v[240:243], v[166:169], v[50:53]
	v_mfma_f32_16x16x32_bf16 v[42:45], v[232:235], v[180:183], v[42:45]
	v_mfma_f32_16x16x32_bf16 v[34:37], v[240:243], v[180:183], v[34:37]
	v_mfma_f32_16x16x32_bf16 v[26:29], v[232:235], v[188:191], v[26:29]
	v_mfma_f32_16x16x32_bf16 v[18:21], v[240:243], v[188:191], v[18:21]
	v_mfma_f32_16x16x32_bf16 v[10:13], v[232:235], v[196:199], v[10:13]
	v_mfma_f32_16x16x32_bf16 v[2:5], v[240:243], v[196:199], v[2:5]
	s_add_i32 s55, s55, 2
	s_add_u32 s44, s44, 0x100
	s_addc_u32 s45, s45, 0
	s_add_u32 s53, s53, 0x100
	s_addc_u32 s54, s54, 0
	s_cmp_gt_u32 s55, 13
	s_barrier
	s_cbranch_scc0 .LBB0_98
	v_mul_f32_e32 v147, 0xbfb8aa3b, v126
	v_exp_f32_e32 v147, v147
	v_readlane_b32 s4, v254, 0
	v_lshl_or_b32 v148, s50, 7, v144
	v_readlane_b32 s5, v254, 1
	v_add_f32_e32 v147, 1.0, v147
	v_rcp_f32_e32 v152, v147
	v_mul_f32_e32 v147, 0xbfb8aa3b, v127
	v_exp_f32_e32 v147, v147
	v_lshl_add_u32 v146, s33, 8, v142
	v_ashrrev_i32_e32 v149, 31, v148
	v_mov_b64_e32 v[140:141], s[4:5]
	v_add_f32_e32 v147, 1.0, v147
	v_rcp_f32_e32 v153, v147
	s_movk_i32 s12, 0x1600
	v_mad_i64_i32 v[150:151], s[4:5], v146, s12, v[140:141]
	v_pk_mul_f32 v[126:127], v[126:127], v[152:153]
	s_and_b64 vcc, exec, s[40:41]
	v_pk_mul_f32 v[122:123], v[126:127], v[122:123]
	v_mul_f32_e32 v126, 0xbfb8aa3b, v128
	v_mul_f32_e32 v127, 0xbfb8aa3b, v129
	v_exp_f32_e32 v126, v126
	v_exp_f32_e32 v127, v127
	s_mov_b32 s50, s24
	s_mov_b32 s33, s22
	v_add_f32_e32 v126, 1.0, v126
	v_add_f32_e32 v127, 1.0, v127
	v_rcp_f32_e32 v126, v126
	v_rcp_f32_e32 v127, v127
	s_mov_b64 s[46:47], s[42:43]
	s_mov_b64 s[44:45], s[38:39]
	v_pk_mul_f32 v[126:127], v[128:129], v[126:127]
	s_nop 0
	v_pk_mul_f32 v[124:125], v[126:127], v[124:125]
	v_mul_f32_e32 v126, 0xbfb8aa3b, v118
	v_mul_f32_e32 v127, 0xbfb8aa3b, v119
	v_exp_f32_e32 v126, v126
	v_exp_f32_e32 v127, v127
	v_add_f32_e32 v126, 1.0, v126
	v_add_f32_e32 v127, 1.0, v127
	v_rcp_f32_e32 v126, v126
	v_rcp_f32_e32 v127, v127
	s_nop 0
	v_pk_mul_f32 v[118:119], v[118:119], v[126:127]
	s_nop 0
	v_pk_mul_f32 v[118:119], v[118:119], v[114:115]
	v_mul_f32_e32 v114, 0xbfb8aa3b, v120
	v_mul_f32_e32 v115, 0xbfb8aa3b, v121
	v_exp_f32_e32 v114, v114
	v_exp_f32_e32 v115, v115
	v_cvt_pk_bf16_f32 v118, v118, v119
	v_add_f32_e32 v114, 1.0, v114
	v_add_f32_e32 v115, 1.0, v115
	v_rcp_f32_e32 v114, v114
	v_rcp_f32_e32 v115, v115
	s_nop 0
	v_pk_mul_f32 v[114:115], v[120:121], v[114:115]
	s_nop 0
	v_pk_mul_f32 v[120:121], v[114:115], v[116:117]
	v_lshlrev_b64 v[114:115], 1, v[148:149]
	v_lshl_add_u64 v[126:127], v[150:151], 0, v[114:115]
	v_cvt_pk_bf16_f32 v116, v122, v123
	v_cvt_pk_bf16_f32 v117, v124, v125
	v_cvt_pk_bf16_f32 v119, v120, v121
	global_store_dwordx4 v[126:127], v[116:119], off sc1
	s_nop 1
	v_mul_f32_e32 v118, 0xbfb8aa3b, v110
	v_mul_f32_e32 v119, 0xbfb8aa3b, v111
	v_exp_f32_e32 v118, v118
	v_exp_f32_e32 v119, v119
	v_or_b32_e32 v116, 16, v146
	v_mad_i64_i32 v[116:117], s[4:5], v116, s12, v[140:141]
	v_add_f32_e32 v118, 1.0, v118
	v_add_f32_e32 v119, 1.0, v119
	v_rcp_f32_e32 v118, v118
	v_rcp_f32_e32 v119, v119
	s_nop 0
	v_pk_mul_f32 v[110:111], v[110:111], v[118:119]
	s_nop 0
	v_pk_mul_f32 v[106:107], v[110:111], v[106:107]
	v_mul_f32_e32 v110, 0xbfb8aa3b, v112
	v_mul_f32_e32 v111, 0xbfb8aa3b, v113
	v_exp_f32_e32 v110, v110
	v_exp_f32_e32 v111, v111
	v_add_f32_e32 v110, 1.0, v110
	v_add_f32_e32 v111, 1.0, v111
	v_rcp_f32_e32 v110, v110
	v_rcp_f32_e32 v111, v111
	s_nop 0
	v_pk_mul_f32 v[110:111], v[112:113], v[110:111]
	s_nop 0
	v_pk_mul_f32 v[108:109], v[110:111], v[108:109]
	v_mul_f32_e32 v110, 0xbfb8aa3b, v102
	v_mul_f32_e32 v111, 0xbfb8aa3b, v103
	v_exp_f32_e32 v110, v110
	v_exp_f32_e32 v111, v111
	v_add_f32_e32 v110, 1.0, v110
	v_add_f32_e32 v111, 1.0, v111
	v_rcp_f32_e32 v110, v110
	v_rcp_f32_e32 v111, v111
	s_nop 0
	v_pk_mul_f32 v[102:103], v[102:103], v[110:111]
	s_nop 0
	v_pk_mul_f32 v[102:103], v[102:103], v[98:99]
	v_mul_f32_e32 v98, 0xbfb8aa3b, v104
	v_mul_f32_e32 v99, 0xbfb8aa3b, v105
	v_exp_f32_e32 v98, v98
	v_exp_f32_e32 v99, v99
	v_lshl_add_u64 v[110:111], v[116:117], 0, v[114:115]
	v_add_f32_e32 v98, 1.0, v98
	v_add_f32_e32 v99, 1.0, v99
	v_rcp_f32_e32 v98, v98
	v_rcp_f32_e32 v99, v99
	s_nop 0
	v_pk_mul_f32 v[98:99], v[104:105], v[98:99]
	s_nop 0
	v_pk_mul_f32 v[104:105], v[98:99], v[100:101]
	v_cvt_pk_bf16_f32 v98, v106, v107
	v_cvt_pk_bf16_f32 v99, v108, v109
	v_cvt_pk_bf16_f32 v100, v102, v103
	v_cvt_pk_bf16_f32 v101, v104, v105
	global_store_dwordx4 v[110:111], v[98:101], off sc1
	s_nop 1
	v_mul_f32_e32 v100, 0xbfb8aa3b, v94
	v_mul_f32_e32 v101, 0xbfb8aa3b, v95
	v_exp_f32_e32 v100, v100
	v_exp_f32_e32 v101, v101
	v_or_b32_e32 v98, 32, v146
	v_mad_i64_i32 v[98:99], s[4:5], v98, s12, v[140:141]
	v_add_f32_e32 v100, 1.0, v100
	v_add_f32_e32 v101, 1.0, v101
	v_rcp_f32_e32 v100, v100
	v_rcp_f32_e32 v101, v101
	s_nop 0
	v_pk_mul_f32 v[94:95], v[94:95], v[100:101]
	s_nop 0
	v_pk_mul_f32 v[90:91], v[94:95], v[90:91]
	v_mul_f32_e32 v94, 0xbfb8aa3b, v96
	v_mul_f32_e32 v95, 0xbfb8aa3b, v97
	v_exp_f32_e32 v94, v94
	v_exp_f32_e32 v95, v95
	v_add_f32_e32 v94, 1.0, v94
	v_add_f32_e32 v95, 1.0, v95
	v_rcp_f32_e32 v94, v94
	v_rcp_f32_e32 v95, v95
	s_nop 0
	v_pk_mul_f32 v[94:95], v[96:97], v[94:95]
	s_nop 0
	v_pk_mul_f32 v[92:93], v[94:95], v[92:93]
	v_mul_f32_e32 v94, 0xbfb8aa3b, v86
	v_mul_f32_e32 v95, 0xbfb8aa3b, v87
	v_exp_f32_e32 v94, v94
	v_exp_f32_e32 v95, v95
	v_add_f32_e32 v94, 1.0, v94
	v_add_f32_e32 v95, 1.0, v95
	v_rcp_f32_e32 v94, v94
	v_rcp_f32_e32 v95, v95
	s_nop 0
	v_pk_mul_f32 v[86:87], v[86:87], v[94:95]
	s_nop 0
	v_pk_mul_f32 v[86:87], v[86:87], v[82:83]
	v_mul_f32_e32 v82, 0xbfb8aa3b, v88
	v_mul_f32_e32 v83, 0xbfb8aa3b, v89
	v_exp_f32_e32 v82, v82
	v_exp_f32_e32 v83, v83
	v_lshl_add_u64 v[94:95], v[98:99], 0, v[114:115]
	v_add_f32_e32 v82, 1.0, v82
	v_add_f32_e32 v83, 1.0, v83
	v_rcp_f32_e32 v82, v82
	v_rcp_f32_e32 v83, v83
	s_nop 0
	v_pk_mul_f32 v[82:83], v[88:89], v[82:83]
	s_nop 0
	v_pk_mul_f32 v[88:89], v[82:83], v[84:85]
	v_cvt_pk_bf16_f32 v82, v90, v91
	v_cvt_pk_bf16_f32 v83, v92, v93
	v_cvt_pk_bf16_f32 v84, v86, v87
	v_cvt_pk_bf16_f32 v85, v88, v89
	global_store_dwordx4 v[94:95], v[82:85], off sc1
	s_nop 1
	v_mul_f32_e32 v84, 0xbfb8aa3b, v78
	v_mul_f32_e32 v85, 0xbfb8aa3b, v79
	v_exp_f32_e32 v84, v84
	v_exp_f32_e32 v85, v85
	v_or_b32_e32 v82, 48, v146
	v_mad_i64_i32 v[82:83], s[4:5], v82, s12, v[140:141]
	v_add_f32_e32 v84, 1.0, v84
	v_add_f32_e32 v85, 1.0, v85
	v_rcp_f32_e32 v84, v84
	v_rcp_f32_e32 v85, v85
	s_nop 0
	v_pk_mul_f32 v[78:79], v[78:79], v[84:85]
	s_nop 0
	v_pk_mul_f32 v[74:75], v[78:79], v[74:75]
	v_mul_f32_e32 v78, 0xbfb8aa3b, v80
	v_mul_f32_e32 v79, 0xbfb8aa3b, v81
	v_exp_f32_e32 v78, v78
	v_exp_f32_e32 v79, v79
	v_add_f32_e32 v78, 1.0, v78
	v_add_f32_e32 v79, 1.0, v79
	v_rcp_f32_e32 v78, v78
	v_rcp_f32_e32 v79, v79
	s_nop 0
	v_pk_mul_f32 v[78:79], v[80:81], v[78:79]
	s_nop 0
	v_pk_mul_f32 v[76:77], v[78:79], v[76:77]
	v_mul_f32_e32 v78, 0xbfb8aa3b, v70
	v_mul_f32_e32 v79, 0xbfb8aa3b, v71
	v_exp_f32_e32 v78, v78
	v_exp_f32_e32 v79, v79
	v_add_f32_e32 v78, 1.0, v78
	v_add_f32_e32 v79, 1.0, v79
	v_rcp_f32_e32 v78, v78
	v_rcp_f32_e32 v79, v79
	s_nop 0
	v_pk_mul_f32 v[70:71], v[70:71], v[78:79]
	s_nop 0
	v_pk_mul_f32 v[70:71], v[70:71], v[66:67]
	v_mul_f32_e32 v66, 0xbfb8aa3b, v72
	v_mul_f32_e32 v67, 0xbfb8aa3b, v73
	v_exp_f32_e32 v66, v66
	v_exp_f32_e32 v67, v67
	v_lshl_add_u64 v[78:79], v[82:83], 0, v[114:115]
	v_add_f32_e32 v66, 1.0, v66
	v_add_f32_e32 v67, 1.0, v67
	v_rcp_f32_e32 v66, v66
	v_rcp_f32_e32 v67, v67
	s_nop 0
	v_pk_mul_f32 v[66:67], v[72:73], v[66:67]
	s_nop 0
	v_pk_mul_f32 v[72:73], v[66:67], v[68:69]
	v_cvt_pk_bf16_f32 v66, v74, v75
	v_cvt_pk_bf16_f32 v67, v76, v77
	v_cvt_pk_bf16_f32 v68, v70, v71
	v_cvt_pk_bf16_f32 v69, v72, v73
	global_store_dwordx4 v[78:79], v[66:69], off sc1
	s_nop 1
	v_mul_f32_e32 v68, 0xbfb8aa3b, v62
	v_mul_f32_e32 v69, 0xbfb8aa3b, v63
	v_exp_f32_e32 v68, v68
	v_exp_f32_e32 v69, v69
	v_add_u32_e32 v66, 0x80, v146
	v_mad_i64_i32 v[66:67], s[4:5], v66, s12, v[140:141]
	v_add_f32_e32 v68, 1.0, v68
	v_add_f32_e32 v69, 1.0, v69
	v_rcp_f32_e32 v68, v68
	v_rcp_f32_e32 v69, v69
	s_nop 0
	v_pk_mul_f32 v[62:63], v[62:63], v[68:69]
	s_nop 0
	v_pk_mul_f32 v[58:59], v[62:63], v[58:59]
	v_mul_f32_e32 v62, 0xbfb8aa3b, v64
	v_mul_f32_e32 v63, 0xbfb8aa3b, v65
	v_exp_f32_e32 v62, v62
	v_exp_f32_e32 v63, v63
	v_add_f32_e32 v62, 1.0, v62
	v_add_f32_e32 v63, 1.0, v63
	v_rcp_f32_e32 v62, v62
	v_rcp_f32_e32 v63, v63
	s_nop 0
	v_pk_mul_f32 v[62:63], v[64:65], v[62:63]
	s_nop 0
	v_pk_mul_f32 v[60:61], v[62:63], v[60:61]
	v_mul_f32_e32 v62, 0xbfb8aa3b, v54
	v_mul_f32_e32 v63, 0xbfb8aa3b, v55
	v_exp_f32_e32 v62, v62
	v_exp_f32_e32 v63, v63
	v_add_f32_e32 v62, 1.0, v62
	v_add_f32_e32 v63, 1.0, v63
	v_rcp_f32_e32 v62, v62
	v_rcp_f32_e32 v63, v63
	s_nop 0
	v_pk_mul_f32 v[54:55], v[54:55], v[62:63]
	s_nop 0
	v_pk_mul_f32 v[54:55], v[54:55], v[50:51]
	v_mul_f32_e32 v50, 0xbfb8aa3b, v56
	v_mul_f32_e32 v51, 0xbfb8aa3b, v57
	v_exp_f32_e32 v50, v50
	v_exp_f32_e32 v51, v51
	v_lshl_add_u64 v[62:63], v[66:67], 0, v[114:115]
	v_add_f32_e32 v50, 1.0, v50
	v_add_f32_e32 v51, 1.0, v51
	v_rcp_f32_e32 v50, v50
	v_rcp_f32_e32 v51, v51
	s_nop 0
	v_pk_mul_f32 v[50:51], v[56:57], v[50:51]
	s_nop 0
	v_pk_mul_f32 v[56:57], v[50:51], v[52:53]
	v_cvt_pk_bf16_f32 v50, v58, v59
	v_cvt_pk_bf16_f32 v51, v60, v61
	v_cvt_pk_bf16_f32 v52, v54, v55
	v_cvt_pk_bf16_f32 v53, v56, v57
	global_store_dwordx4 v[62:63], v[50:53], off sc1
	s_nop 1
	v_mul_f32_e32 v52, 0xbfb8aa3b, v46
	v_mul_f32_e32 v53, 0xbfb8aa3b, v47
	v_exp_f32_e32 v52, v52
	v_exp_f32_e32 v53, v53
	v_add_u32_e32 v50, 0x90, v146
	v_mad_i64_i32 v[50:51], s[4:5], v50, s12, v[140:141]
	v_add_f32_e32 v52, 1.0, v52
	v_add_f32_e32 v53, 1.0, v53
	v_rcp_f32_e32 v52, v52
	v_rcp_f32_e32 v53, v53
	s_nop 0
	v_pk_mul_f32 v[46:47], v[46:47], v[52:53]
	s_nop 0
	v_pk_mul_f32 v[42:43], v[46:47], v[42:43]
	v_mul_f32_e32 v46, 0xbfb8aa3b, v48
	v_mul_f32_e32 v47, 0xbfb8aa3b, v49
	v_exp_f32_e32 v46, v46
	v_exp_f32_e32 v47, v47
	v_add_f32_e32 v46, 1.0, v46
	v_add_f32_e32 v47, 1.0, v47
	v_rcp_f32_e32 v46, v46
	v_rcp_f32_e32 v47, v47
	s_nop 0
	v_pk_mul_f32 v[46:47], v[48:49], v[46:47]
	s_nop 0
	v_pk_mul_f32 v[44:45], v[46:47], v[44:45]
	v_mul_f32_e32 v46, 0xbfb8aa3b, v38
	v_mul_f32_e32 v47, 0xbfb8aa3b, v39
	v_exp_f32_e32 v46, v46
	v_exp_f32_e32 v47, v47
	v_add_f32_e32 v46, 1.0, v46
	v_add_f32_e32 v47, 1.0, v47
	v_rcp_f32_e32 v46, v46
	v_rcp_f32_e32 v47, v47
	s_nop 0
	v_pk_mul_f32 v[38:39], v[38:39], v[46:47]
	s_nop 0
	v_pk_mul_f32 v[38:39], v[38:39], v[34:35]
	v_mul_f32_e32 v34, 0xbfb8aa3b, v40
	v_mul_f32_e32 v35, 0xbfb8aa3b, v41
	v_exp_f32_e32 v34, v34
	v_exp_f32_e32 v35, v35
	v_lshl_add_u64 v[46:47], v[50:51], 0, v[114:115]
	v_add_f32_e32 v34, 1.0, v34
	v_add_f32_e32 v35, 1.0, v35
	v_rcp_f32_e32 v34, v34
	v_rcp_f32_e32 v35, v35
	s_nop 0
	v_pk_mul_f32 v[34:35], v[40:41], v[34:35]
	s_nop 0
	v_pk_mul_f32 v[40:41], v[34:35], v[36:37]
	v_cvt_pk_bf16_f32 v34, v42, v43
	v_cvt_pk_bf16_f32 v35, v44, v45
	v_cvt_pk_bf16_f32 v36, v38, v39
	v_cvt_pk_bf16_f32 v37, v40, v41
	global_store_dwordx4 v[46:47], v[34:37], off sc1
	s_nop 1
	v_mul_f32_e32 v36, 0xbfb8aa3b, v30
	v_mul_f32_e32 v37, 0xbfb8aa3b, v31
	v_exp_f32_e32 v36, v36
	v_exp_f32_e32 v37, v37
	v_add_u32_e32 v34, 0xa0, v146
	v_mad_i64_i32 v[34:35], s[4:5], v34, s12, v[140:141]
	v_add_f32_e32 v36, 1.0, v36
	v_add_f32_e32 v37, 1.0, v37
	v_rcp_f32_e32 v36, v36
	v_rcp_f32_e32 v37, v37
	s_nop 0
	v_pk_mul_f32 v[30:31], v[30:31], v[36:37]
	s_nop 0
	v_pk_mul_f32 v[26:27], v[30:31], v[26:27]
	v_mul_f32_e32 v30, 0xbfb8aa3b, v32
	v_mul_f32_e32 v31, 0xbfb8aa3b, v33
	v_exp_f32_e32 v30, v30
	v_exp_f32_e32 v31, v31
	v_add_f32_e32 v30, 1.0, v30
	v_add_f32_e32 v31, 1.0, v31
	v_rcp_f32_e32 v30, v30
	v_rcp_f32_e32 v31, v31
	s_nop 0
	v_pk_mul_f32 v[30:31], v[32:33], v[30:31]
	s_nop 0
	v_pk_mul_f32 v[28:29], v[30:31], v[28:29]
	v_mul_f32_e32 v30, 0xbfb8aa3b, v22
	v_mul_f32_e32 v31, 0xbfb8aa3b, v23
	v_exp_f32_e32 v30, v30
	v_exp_f32_e32 v31, v31
	v_add_f32_e32 v30, 1.0, v30
	v_add_f32_e32 v31, 1.0, v31
	v_rcp_f32_e32 v30, v30
	v_rcp_f32_e32 v31, v31
	s_nop 0
	v_pk_mul_f32 v[22:23], v[22:23], v[30:31]
	s_nop 0
	v_pk_mul_f32 v[22:23], v[22:23], v[18:19]
	v_mul_f32_e32 v18, 0xbfb8aa3b, v24
	v_mul_f32_e32 v19, 0xbfb8aa3b, v25
	v_exp_f32_e32 v18, v18
	v_exp_f32_e32 v19, v19
	v_lshl_add_u64 v[30:31], v[34:35], 0, v[114:115]
	v_add_f32_e32 v18, 1.0, v18
	v_add_f32_e32 v19, 1.0, v19
	v_rcp_f32_e32 v18, v18
	v_rcp_f32_e32 v19, v19
	s_nop 0
	v_pk_mul_f32 v[18:19], v[24:25], v[18:19]
	s_nop 0
	v_pk_mul_f32 v[24:25], v[18:19], v[20:21]
	v_cvt_pk_bf16_f32 v18, v26, v27
	v_cvt_pk_bf16_f32 v19, v28, v29
	v_cvt_pk_bf16_f32 v20, v22, v23
	v_cvt_pk_bf16_f32 v21, v24, v25
	global_store_dwordx4 v[30:31], v[18:21], off sc1
	s_nop 1
	v_mul_f32_e32 v20, 0xbfb8aa3b, v14
	v_mul_f32_e32 v21, 0xbfb8aa3b, v15
	v_exp_f32_e32 v20, v20
	v_exp_f32_e32 v21, v21
	v_add_u32_e32 v18, 0xb0, v146
	v_mad_i64_i32 v[18:19], s[4:5], v18, s12, v[140:141]
	v_add_f32_e32 v20, 1.0, v20
	v_add_f32_e32 v21, 1.0, v21
	v_rcp_f32_e32 v20, v20
	v_rcp_f32_e32 v21, v21
	s_nop 0
	v_pk_mul_f32 v[14:15], v[14:15], v[20:21]
	s_nop 0
	v_pk_mul_f32 v[10:11], v[14:15], v[10:11]
	v_mul_f32_e32 v14, 0xbfb8aa3b, v16
	v_mul_f32_e32 v15, 0xbfb8aa3b, v17
	v_exp_f32_e32 v14, v14
	v_exp_f32_e32 v15, v15
	v_add_f32_e32 v14, 1.0, v14
	v_add_f32_e32 v15, 1.0, v15
	v_rcp_f32_e32 v14, v14
	v_rcp_f32_e32 v15, v15
	s_nop 0
	v_pk_mul_f32 v[14:15], v[16:17], v[14:15]
	s_nop 0
	v_pk_mul_f32 v[12:13], v[14:15], v[12:13]
	v_mul_f32_e32 v14, 0xbfb8aa3b, v6
	v_mul_f32_e32 v15, 0xbfb8aa3b, v7
	v_exp_f32_e32 v14, v14
	v_exp_f32_e32 v15, v15
	v_add_f32_e32 v14, 1.0, v14
	v_add_f32_e32 v15, 1.0, v15
	v_rcp_f32_e32 v14, v14
	v_rcp_f32_e32 v15, v15
	s_nop 0
	v_pk_mul_f32 v[6:7], v[6:7], v[14:15]
	s_nop 0
	v_pk_mul_f32 v[6:7], v[6:7], v[2:3]
	v_mul_f32_e32 v2, 0xbfb8aa3b, v8
	v_mul_f32_e32 v3, 0xbfb8aa3b, v9
	v_exp_f32_e32 v2, v2
	v_exp_f32_e32 v3, v3
	v_lshl_add_u64 v[14:15], v[18:19], 0, v[114:115]
	v_add_f32_e32 v2, 1.0, v2
	v_add_f32_e32 v3, 1.0, v3
	v_rcp_f32_e32 v2, v2
	v_rcp_f32_e32 v3, v3
	s_nop 0
	v_pk_mul_f32 v[2:3], v[8:9], v[2:3]
	s_nop 0
	v_pk_mul_f32 v[8:9], v[2:3], v[4:5]
	v_cvt_pk_bf16_f32 v2, v10, v11
	v_cvt_pk_bf16_f32 v3, v12, v13
	v_cvt_pk_bf16_f32 v4, v6, v7
	v_cvt_pk_bf16_f32 v5, v8, v9
	global_store_dwordx4 v[14:15], v[2:5], off sc1
	s_cbranch_vccz .LBB0_95
	s_waitcnt vmcnt(0)
	s_cmpk_gt_u32 s3, 0xff
	s_cbranch_scc1 .LBB0_102
	s_barrier

.LBB0_841:
	s_add_i32 vcc_lo, s71, 2
	s_add_u32 s16, s42, 0x80
	s_addc_u32 s17, s43, 0
	s_add_i32 s84, 0, 0x10000
	v_add_u32_e32 v156, s84, v145
	ds_read_b128 v[140:143], v156
	ds_read_b128 v[148:151], v156 offset:1024
	ds_read_b128 v[152:155], v156 offset:2048
	ds_read_b128 v[156:159], v156 offset:3072
	s_cmp_eq_u32 s12, s71
	s_cselect_b32 s75, s73, s17
	s_cselect_b32 s74, s72, s16
	s_cselect_b32 s77, s45, s15
	s_cselect_b32 s76, s44, s14
	v_lshl_add_u64 v[168:169], s[42:43], 0, v[136:137]
	s_add_i32 m0, s91, 0xc000
	ds_read_b128 v[160:163], v147
	ds_read_b128 v[164:167], v147 offset:1024
	ds_read_b128 v[176:179], v147 offset:2048
	ds_read_b128 v[180:183], v147 offset:3072
	ds_read_b128 v[184:187], v147 offset:4096
	ds_read_b128 v[188:191], v147 offset:5120
	ds_read_b128 v[192:195], v147 offset:6144
	ds_read_b128 v[196:199], v147 offset:7168
	global_load_lds_dwordx4 v[168:169], off
	v_lshl_add_u64 v[168:169], s[42:43], 0, v[138:139]
	s_add_i32 m0, s91, 0xe000
	s_nop 0
	global_load_lds_dwordx4 v[168:169], off
	s_waitcnt lgkmcnt(8)
	s_barrier
	s_waitcnt lgkmcnt(0)
	s_waitcnt lgkmcnt(0)
	v_mfma_f32_16x16x32_bf16 v[126:129], v[140:143], v[160:163], v[126:129]
	v_mfma_f32_16x16x32_bf16 v[122:125], v[152:155], v[160:163], v[122:125]
	v_mfma_f32_16x16x32_bf16 v[114:117], v[140:143], v[176:179], v[114:117]
	v_mfma_f32_16x16x32_bf16 v[106:109], v[152:155], v[176:179], v[106:109]
	v_mfma_f32_16x16x32_bf16 v[98:101], v[140:143], v[184:187], v[98:101]
	v_mfma_f32_16x16x32_bf16 v[90:93], v[152:155], v[184:187], v[90:93]
	v_mfma_f32_16x16x32_bf16 v[82:85], v[140:143], v[192:195], v[82:85]
	v_mfma_f32_16x16x32_bf16 v[74:77], v[152:155], v[192:195], v[74:77]
	v_mfma_f32_16x16x32_bf16 v[126:129], v[148:151], v[164:167], v[126:129]
	v_mfma_f32_16x16x32_bf16 v[122:125], v[156:159], v[164:167], v[122:125]
	v_mfma_f32_16x16x32_bf16 v[114:117], v[148:151], v[180:183], v[114:117]
	v_mfma_f32_16x16x32_bf16 v[106:109], v[156:159], v[180:183], v[106:109]
	v_mfma_f32_16x16x32_bf16 v[98:101], v[148:151], v[188:191], v[98:101]
	v_mfma_f32_16x16x32_bf16 v[90:93], v[156:159], v[188:191], v[90:93]
	v_mfma_f32_16x16x32_bf16 v[82:85], v[148:151], v[196:199], v[82:85]
	v_mfma_f32_16x16x32_bf16 v[74:77], v[156:159], v[196:199], v[74:77]
	s_barrier
	s_add_i32 s16, 0, 0x14000
	v_add_u32_e32 v168, s16, v145
	s_add_i32 s17, s84, s87
	ds_read_b128 v[228:231], v168
	ds_read_b128 v[232:235], v168 offset:1024
	ds_read_b128 v[236:239], v168 offset:2048
	ds_read_b128 v[240:243], v168 offset:3072
	v_lshl_add_u64 v[168:169], s[76:77], 0, v[0:1]
	s_mov_b32 m0, s17
	v_lshl_add_u64 v[200:201], s[76:77], 0, v[134:135]
	global_load_lds_dwordx4 v[168:169], off
	s_add_i32 m0, s17, 0x2000
	s_nop 0
	global_load_lds_dwordx4 v[200:201], off
	s_barrier
	s_waitcnt lgkmcnt(0)
	s_waitcnt lgkmcnt(0)
	v_mfma_f32_16x16x32_bf16 v[118:121], v[228:231], v[160:163], v[118:121]
	v_mfma_f32_16x16x32_bf16 v[110:113], v[236:239], v[160:163], v[110:113]
	v_mfma_f32_16x16x32_bf16 v[102:105], v[228:231], v[176:179], v[102:105]
	v_mfma_f32_16x16x32_bf16 v[94:97], v[236:239], v[176:179], v[94:97]
	v_mfma_f32_16x16x32_bf16 v[86:89], v[228:231], v[184:187], v[86:89]
	v_mfma_f32_16x16x32_bf16 v[78:81], v[236:239], v[184:187], v[78:81]
	v_mfma_f32_16x16x32_bf16 v[70:73], v[228:231], v[192:195], v[70:73]
	v_mfma_f32_16x16x32_bf16 v[66:69], v[236:239], v[192:195], v[66:69]
	v_mfma_f32_16x16x32_bf16 v[118:121], v[232:235], v[164:167], v[118:121]
	v_mfma_f32_16x16x32_bf16 v[110:113], v[240:243], v[164:167], v[110:113]
	v_mfma_f32_16x16x32_bf16 v[102:105], v[232:235], v[180:183], v[102:105]
	v_mfma_f32_16x16x32_bf16 v[94:97], v[240:243], v[180:183], v[94:97]
	v_mfma_f32_16x16x32_bf16 v[86:89], v[232:235], v[188:191], v[86:89]
	v_mfma_f32_16x16x32_bf16 v[78:81], v[240:243], v[188:191], v[78:81]
	v_mfma_f32_16x16x32_bf16 v[70:73], v[232:235], v[196:199], v[70:73]
	v_mfma_f32_16x16x32_bf16 v[66:69], v[240:243], v[196:199], v[66:69]
	s_mov_b32 m0, s91
	v_lshl_add_u64 v[244:245], s[74:75], 0, v[130:131]
	s_barrier
	ds_read_b128 v[160:163], v147 offset:16384
	ds_read_b128 v[164:167], v147 offset:17408
	ds_read_b128 v[176:179], v147 offset:18432
	ds_read_b128 v[180:183], v147 offset:19456
	ds_read_b128 v[184:187], v147 offset:20480
	ds_read_b128 v[188:191], v147 offset:21504
	ds_read_b128 v[192:195], v147 offset:22528
	ds_read_b128 v[196:199], v147 offset:23552
	global_load_lds_dwordx4 v[244:245], off
	v_lshl_add_u64 v[246:247], s[74:75], 0, v[132:133]
	s_mov_b32 m0, s92
	s_nop 0
	global_load_lds_dwordx4 v[246:247], off
	s_barrier
	s_waitcnt lgkmcnt(0)
	s_waitcnt lgkmcnt(0)
	v_mfma_f32_16x16x32_bf16 v[62:65], v[140:143], v[160:163], v[62:65]
	v_mfma_f32_16x16x32_bf16 v[58:61], v[152:155], v[160:163], v[58:61]
	v_mfma_f32_16x16x32_bf16 v[54:57], v[140:143], v[176:179], v[54:57]
	v_mfma_f32_16x16x32_bf16 v[46:49], v[152:155], v[176:179], v[46:49]
	v_mfma_f32_16x16x32_bf16 v[38:41], v[140:143], v[184:187], v[38:41]
	v_mfma_f32_16x16x32_bf16 v[30:33], v[152:155], v[184:187], v[30:33]
	v_mfma_f32_16x16x32_bf16 v[22:25], v[140:143], v[192:195], v[22:25]
	v_mfma_f32_16x16x32_bf16 v[14:17], v[152:155], v[192:195], v[14:17]
	v_mfma_f32_16x16x32_bf16 v[62:65], v[148:151], v[164:167], v[62:65]
	v_mfma_f32_16x16x32_bf16 v[58:61], v[156:159], v[164:167], v[58:61]
	v_mfma_f32_16x16x32_bf16 v[54:57], v[148:151], v[180:183], v[54:57]
	v_mfma_f32_16x16x32_bf16 v[46:49], v[156:159], v[180:183], v[46:49]
	v_mfma_f32_16x16x32_bf16 v[38:41], v[148:151], v[188:191], v[38:41]
	v_mfma_f32_16x16x32_bf16 v[30:33], v[156:159], v[188:191], v[30:33]
	v_mfma_f32_16x16x32_bf16 v[22:25], v[148:151], v[196:199], v[22:25]
	v_mfma_f32_16x16x32_bf16 v[14:17], v[156:159], v[196:199], v[14:17]
	s_barrier
	s_add_u32 s76, s76, s64
	s_addc_u32 s77, s77, 0
	s_add_i32 s16, s16, s87
	v_lshl_add_u64 v[248:249], s[76:77], 0, v[0:1]
	s_mov_b32 m0, s16
	v_lshl_add_u64 v[250:251], s[76:77], 0, v[134:135]
	global_load_lds_dwordx4 v[248:249], off
	s_add_i32 m0, s16, 0x2000
	s_nop 0
	global_load_lds_dwordx4 v[250:251], off
	s_waitcnt vmcnt(6)
	s_barrier
	v_mfma_f32_16x16x32_bf16 v[50:53], v[228:231], v[160:163], v[50:53]
	v_mfma_f32_16x16x32_bf16 v[42:45], v[236:239], v[160:163], v[42:45]
	v_mfma_f32_16x16x32_bf16 v[34:37], v[228:231], v[176:179], v[34:37]
	v_mfma_f32_16x16x32_bf16 v[26:29], v[236:239], v[176:179], v[26:29]
	v_mfma_f32_16x16x32_bf16 v[18:21], v[228:231], v[184:187], v[18:21]
	v_mfma_f32_16x16x32_bf16 v[10:13], v[236:239], v[184:187], v[10:13]
	v_mfma_f32_16x16x32_bf16 v[6:9], v[228:231], v[192:195], v[6:9]
	v_mfma_f32_16x16x32_bf16 v[2:5], v[236:239], v[192:195], v[2:5]
	v_mfma_f32_16x16x32_bf16 v[50:53], v[232:235], v[164:167], v[50:53]
	v_mfma_f32_16x16x32_bf16 v[42:45], v[240:243], v[164:167], v[42:45]
	v_mfma_f32_16x16x32_bf16 v[34:37], v[232:235], v[180:183], v[34:37]
	v_mfma_f32_16x16x32_bf16 v[26:29], v[240:243], v[180:183], v[26:29]
	v_mfma_f32_16x16x32_bf16 v[18:21], v[232:235], v[188:191], v[18:21]
	v_mfma_f32_16x16x32_bf16 v[10:13], v[240:243], v[188:191], v[10:13]
	v_mfma_f32_16x16x32_bf16 v[6:9], v[232:235], v[196:199], v[6:9]
	v_mfma_f32_16x16x32_bf16 v[2:5], v[240:243], v[196:199], v[2:5]
	s_add_i32 s16, 0, 0x18000
	v_add_u32_e32 v156, s16, v145
	s_barrier
	ds_read_b128 v[140:143], v156
	ds_read_b128 v[148:151], v156 offset:1024
	ds_read_b128 v[152:155], v156 offset:2048
	ds_read_b128 v[156:159], v156 offset:3072
	s_add_u32 s74, s74, s64
	s_addc_u32 s75, s75, 0
	s_mov_b32 m0, s93
	v_lshl_add_u64 v[228:229], s[74:75], 0, v[130:131]
	ds_read_b128 v[160:163], v147 offset:32768
	ds_read_b128 v[164:167], v147 offset:33792
	ds_read_b128 v[176:179], v147 offset:34816
	ds_read_b128 v[180:183], v147 offset:35840
	ds_read_b128 v[184:187], v147 offset:36864
	ds_read_b128 v[188:191], v147 offset:37888
	ds_read_b128 v[192:195], v147 offset:38912
	ds_read_b128 v[196:199], v147 offset:39936
	global_load_lds_dwordx4 v[228:229], off
	v_lshl_add_u64 v[228:229], s[74:75], 0, v[132:133]
	s_mov_b32 m0, s94
	s_nop 0
	global_load_lds_dwordx4 v[228:229], off
	s_waitcnt lgkmcnt(8)
	s_barrier
	s_waitcnt lgkmcnt(0)
	s_waitcnt lgkmcnt(0)
	v_mfma_f32_16x16x32_bf16 v[126:129], v[140:143], v[160:163], v[126:129]
	v_mfma_f32_16x16x32_bf16 v[122:125], v[152:155], v[160:163], v[122:125]
	v_mfma_f32_16x16x32_bf16 v[114:117], v[140:143], v[176:179], v[114:117]
	v_mfma_f32_16x16x32_bf16 v[106:109], v[152:155], v[176:179], v[106:109]
	v_mfma_f32_16x16x32_bf16 v[98:101], v[140:143], v[184:187], v[98:101]
	v_mfma_f32_16x16x32_bf16 v[90:93], v[152:155], v[184:187], v[90:93]
	v_mfma_f32_16x16x32_bf16 v[82:85], v[140:143], v[192:195], v[82:85]
	v_mfma_f32_16x16x32_bf16 v[74:77], v[152:155], v[192:195], v[74:77]
	v_mfma_f32_16x16x32_bf16 v[126:129], v[148:151], v[164:167], v[126:129]
	v_mfma_f32_16x16x32_bf16 v[122:125], v[156:159], v[164:167], v[122:125]
	v_mfma_f32_16x16x32_bf16 v[114:117], v[148:151], v[180:183], v[114:117]
	v_mfma_f32_16x16x32_bf16 v[106:109], v[156:159], v[180:183], v[106:109]
	v_mfma_f32_16x16x32_bf16 v[98:101], v[148:151], v[188:191], v[98:101]
	v_mfma_f32_16x16x32_bf16 v[90:93], v[156:159], v[188:191], v[90:93]
	v_mfma_f32_16x16x32_bf16 v[82:85], v[148:151], v[196:199], v[82:85]
	v_mfma_f32_16x16x32_bf16 v[74:77], v[156:159], v[196:199], v[74:77]
	s_barrier
	s_add_i32 s17, 0, 0x1c000
	s_add_i32 s16, s16, s87
	v_add_u32_e32 v175, s17, v145
	v_lshl_add_u64 v[168:169], v[168:169], 0, s[34:35]
	s_mov_b32 m0, s16
	ds_read_b128 v[228:231], v175
	ds_read_b128 v[232:235], v175 offset:1024
	ds_read_b128 v[236:239], v175 offset:2048
	ds_read_b128 v[240:243], v175 offset:3072
	global_load_lds_dwordx4 v[168:169], off
	v_lshl_add_u64 v[168:169], v[200:201], 0, s[34:35]
	s_add_i32 m0, s16, 0x2000
	s_nop 0
	global_load_lds_dwordx4 v[168:169], off
	s_barrier
	s_waitcnt lgkmcnt(0)
	s_waitcnt lgkmcnt(0)
	v_mfma_f32_16x16x32_bf16 v[118:121], v[228:231], v[160:163], v[118:121]
	v_mfma_f32_16x16x32_bf16 v[110:113], v[236:239], v[160:163], v[110:113]
	v_mfma_f32_16x16x32_bf16 v[102:105], v[228:231], v[176:179], v[102:105]
	v_mfma_f32_16x16x32_bf16 v[94:97], v[236:239], v[176:179], v[94:97]
	v_mfma_f32_16x16x32_bf16 v[86:89], v[228:231], v[184:187], v[86:89]
	v_mfma_f32_16x16x32_bf16 v[78:81], v[236:239], v[184:187], v[78:81]
	v_mfma_f32_16x16x32_bf16 v[70:73], v[228:231], v[192:195], v[70:73]
	v_mfma_f32_16x16x32_bf16 v[66:69], v[236:239], v[192:195], v[66:69]
	v_mfma_f32_16x16x32_bf16 v[118:121], v[232:235], v[164:167], v[118:121]
	v_mfma_f32_16x16x32_bf16 v[110:113], v[240:243], v[164:167], v[110:113]
	v_mfma_f32_16x16x32_bf16 v[102:105], v[232:235], v[180:183], v[102:105]
	v_mfma_f32_16x16x32_bf16 v[94:97], v[240:243], v[180:183], v[94:97]
	v_mfma_f32_16x16x32_bf16 v[86:89], v[232:235], v[188:191], v[86:89]
	v_mfma_f32_16x16x32_bf16 v[78:81], v[240:243], v[188:191], v[78:81]
	v_mfma_f32_16x16x32_bf16 v[70:73], v[232:235], v[196:199], v[70:73]
	v_mfma_f32_16x16x32_bf16 v[66:69], v[240:243], v[196:199], v[66:69]
	s_mov_b32 m0, s96
	v_lshl_add_u64 v[168:169], v[244:245], 0, s[34:35]
	s_barrier
	ds_read_b128 v[160:163], v147 offset:49152
	ds_read_b128 v[164:167], v147 offset:50176
	ds_read_b128 v[176:179], v147 offset:51200
	ds_read_b128 v[180:183], v147 offset:52224
	ds_read_b128 v[184:187], v147 offset:53248
	ds_read_b128 v[188:191], v147 offset:54272
	ds_read_b128 v[192:195], v147 offset:55296
	ds_read_b128 v[196:199], v147 offset:56320
	global_load_lds_dwordx4 v[168:169], off
	v_lshl_add_u64 v[168:169], v[246:247], 0, s[34:35]
	s_mov_b32 m0, s97
	s_nop 0
	global_load_lds_dwordx4 v[168:169], off
	s_barrier
	s_waitcnt lgkmcnt(0)
	s_waitcnt lgkmcnt(0)
	v_mfma_f32_16x16x32_bf16 v[62:65], v[140:143], v[160:163], v[62:65]
	v_mfma_f32_16x16x32_bf16 v[58:61], v[152:155], v[160:163], v[58:61]
	v_mfma_f32_16x16x32_bf16 v[54:57], v[140:143], v[176:179], v[54:57]
	v_mfma_f32_16x16x32_bf16 v[46:49], v[152:155], v[176:179], v[46:49]
	v_mfma_f32_16x16x32_bf16 v[38:41], v[140:143], v[184:187], v[38:41]
	v_mfma_f32_16x16x32_bf16 v[30:33], v[152:155], v[184:187], v[30:33]
	v_mfma_f32_16x16x32_bf16 v[22:25], v[140:143], v[192:195], v[22:25]
	v_mfma_f32_16x16x32_bf16 v[14:17], v[152:155], v[192:195], v[14:17]
	v_mfma_f32_16x16x32_bf16 v[62:65], v[148:151], v[164:167], v[62:65]
	v_mfma_f32_16x16x32_bf16 v[58:61], v[156:159], v[164:167], v[58:61]
	v_mfma_f32_16x16x32_bf16 v[54:57], v[148:151], v[180:183], v[54:57]
	v_mfma_f32_16x16x32_bf16 v[46:49], v[156:159], v[180:183], v[46:49]
	v_mfma_f32_16x16x32_bf16 v[38:41], v[148:151], v[188:191], v[38:41]
	v_mfma_f32_16x16x32_bf16 v[30:33], v[156:159], v[188:191], v[30:33]
	v_mfma_f32_16x16x32_bf16 v[22:25], v[148:151], v[196:199], v[22:25]
	v_mfma_f32_16x16x32_bf16 v[14:17], v[156:159], v[196:199], v[14:17]
	s_barrier
	s_add_i32 s16, s17, s87
	v_lshl_add_u64 v[140:141], v[248:249], 0, s[34:35]
	s_mov_b32 m0, s16
	s_nop 0
	global_load_lds_dwordx4 v[140:141], off
	v_lshl_add_u64 v[140:141], v[250:251], 0, s[34:35]
	s_add_i32 m0, s16, 0x2000
	s_nop 0
	global_load_lds_dwordx4 v[140:141], off
	s_waitcnt vmcnt(6)
	s_barrier
	v_mfma_f32_16x16x32_bf16 v[50:53], v[228:231], v[160:163], v[50:53]
	v_mfma_f32_16x16x32_bf16 v[42:45], v[236:239], v[160:163], v[42:45]
	v_mfma_f32_16x16x32_bf16 v[34:37], v[228:231], v[176:179], v[34:37]
	v_mfma_f32_16x16x32_bf16 v[26:29], v[236:239], v[176:179], v[26:29]
	v_mfma_f32_16x16x32_bf16 v[18:21], v[228:231], v[184:187], v[18:21]
	v_mfma_f32_16x16x32_bf16 v[10:13], v[236:239], v[184:187], v[10:13]
	v_mfma_f32_16x16x32_bf16 v[6:9], v[228:231], v[192:195], v[6:9]
	v_mfma_f32_16x16x32_bf16 v[2:5], v[236:239], v[192:195], v[2:5]
	v_mfma_f32_16x16x32_bf16 v[50:53], v[232:235], v[164:167], v[50:53]
	v_mfma_f32_16x16x32_bf16 v[42:45], v[240:243], v[164:167], v[42:45]
	v_mfma_f32_16x16x32_bf16 v[34:37], v[232:235], v[180:183], v[34:37]
	v_mfma_f32_16x16x32_bf16 v[26:29], v[240:243], v[180:183], v[26:29]
	v_mfma_f32_16x16x32_bf16 v[18:21], v[232:235], v[188:191], v[18:21]
	v_mfma_f32_16x16x32_bf16 v[10:13], v[240:243], v[188:191], v[10:13]
	v_mfma_f32_16x16x32_bf16 v[6:9], v[232:235], v[196:199], v[6:9]
	v_mfma_f32_16x16x32_bf16 v[2:5], v[240:243], v[196:199], v[2:5]
	s_add_u32 s42, s42, 0x100
	s_addc_u32 s43, s43, 0
	s_add_u32 s14, s14, 0x100
	s_addc_u32 s15, s15, 0
	s_cmp_ge_u32 vcc_lo, s18
	s_mov_b32 s71, vcc_lo
	s_barrier
	s_cbranch_scc0 .LBB0_841
	s_mul_hi_i32 s15, s60, s95
	s_mul_i32 s14, s60, s95
	s_lshl_b64 s[14:15], s[14:15], 1
	v_lshl_add_u32 v148, s83, 8, v144
	s_add_u32 s74, s58, s14
	v_lshl_or_b32 v140, s82, 8, v146
	s_addc_u32 s75, s59, s15
	v_mad_i64_i32 v[142:143], s[14:15], v148, s21, 0
	v_lshl_add_u64 v[142:143], v[142:143], 1, s[74:75]
	v_cmp_gt_i32_e32 vcc, s19, v140
	v_ashrrev_i32_e32 v141, 31, v140
	s_and_saveexec_b64 s[14:15], vcc
	s_cbranch_execz .LBB0_844
	v_cvt_pk_bf16_f32 v126, v126, v127
	v_cvt_pk_bf16_f32 v127, v128, v129
	v_cvt_pk_bf16_f32 v128, v122, v123
	v_cvt_pk_bf16_f32 v129, v124, v125
	v_lshl_add_u64 v[122:123], v[140:141], 1, v[142:143]
	global_store_dwordx4 v[122:123], v[126:129], off sc1
